# all 13 grid syncs are now group barriers: compress stage-2 rows re-dealt so each block keeps its own batch (blockIdx%8), last two full barriers converted
# speedup vs baseline: 1.0761x; 1.0138x over previous
.LBB0_968:
	s_mov_b64 s[4:5], s[68:69]
	s_waitcnt vmcnt(0)
	s_waitcnt vmcnt(0) lgkmcnt(0)
	s_barrier
	s_and_saveexec_b64 s[2:3], s[70:71]
	v_readlane_b32 s48, v251, 9
	s_cbranch_execz .LBB0_1020
	v_writelane_b32 v250, s8, 44
	v_writelane_b32 v250, s9, 45
	v_writelane_b32 v250, s10, 46
	v_writelane_b32 v250, s11, 47
	v_writelane_b32 v250, s12, 48
	v_writelane_b32 v250, s13, 49
	v_writelane_b32 v250, s14, 50
	v_writelane_b32 v250, s15, 51
	s_load_dwordx2 s[8:9], s[68:69], 0xb8
	v_readfirstlane_b32 s12, v0
	v_readfirstlane_b32 s13, v1
	v_readlane_b32 s10, v250, 63
	v_readlane_b32 s11, v250, 61
	v_readlane_b32 s14, v250, 59
	v_mov_b32_e32 v0, 0
	s_mov_b32 s15, 0
	s_waitcnt lgkmcnt(0)
	s_add_u32 s8, s8, s10
	s_addc_u32 s9, s9, 0
	s_cmp_lg_u32 s11, 0
	s_cbranch_scc1 .Lgb5_known
	global_load_dword v1, v0, s[8:9] offset:128 sc1
	s_waitcnt vmcnt(0)
	v_readfirstlane_b32 s10, v1
	s_sub_u32 s11, s10, 1
	s_and_b32 s11, s11, s10
	s_cmp_eq_u32 s11, 0
	s_cselect_b32 s11, 2, 1
	s_cmp_eq_u32 s10, 0
	s_cselect_b32 s11, 1, s11
	v_writelane_b32 v250, s11, 61
	s_nop 0

.Lgb5_done:
	v_mov_b32_e32 v0, s12
	v_mov_b32_e32 v1, s13
	v_readlane_b32 s8, v250, 44
	v_readlane_b32 s9, v250, 45
	v_readlane_b32 s10, v250, 46
	v_readlane_b32 s11, v250, 47
	v_readlane_b32 s12, v250, 48
	v_readlane_b32 s13, v250, 49
	v_readlane_b32 s14, v250, 50
	v_readlane_b32 s15, v250, 51
.LBB0_1020:
	s_or_b64 exec, exec, s[2:3]
	s_mov_b64 s[0:1], s[68:69]
	s_waitcnt lgkmcnt(0)
	s_barrier
	s_load_dwordx2 s[4:5], s[0:1], 0xb8
	s_mov_b64 s[0:1], s[68:69]
	s_load_dwordx2 s[6:7], s[0:1], 0xb8
	s_mov_b64 s[12:13], s[68:69]
	s_mov_b64 s[0:1], s[68:69]
	s_load_dwordx2 s[8:9], s[0:1], 0xb8
	s_mov_b64 s[0:1], s[68:69]
	s_load_dwordx2 s[10:11], s[0:1], 0xb8
	v_mov_b32_e32 v4, v196
	v_mov_b32_e32 v5, v196
	v_mov_b32_e32 v0, v196
	s_nop 0
	v_cmp_gt_i32_e32 vcc, s67, v0
	s_and_saveexec_b64 s[2:3], vcc
	s_mov_b64 s[20:21], 0x800
	s_cbranch_execz .LBB0_1028
	s_load_dwordx2 s[12:13], s[12:13], 0x98
	v_readlane_b32 s0, v251, 63
	v_lshlrev_b32_e32 v1, 4, v0
	s_waitcnt lgkmcnt(0)
	s_add_u32 s16, s12, s0
	s_addc_u32 s17, s13, 0
	global_load_dwordx4 v[6:9], v1, s[16:17]
	v_add_u32_e32 v2, 0x2000, v1
	global_load_dwordx4 v[10:13], v2, s[16:17]
	v_add_u32_e32 v3, 0x4000, v1
	global_load_dwordx4 v[14:17], v3, s[16:17]
	v_add_u32_e32 v38, 0x6000, v1
	global_load_dwordx4 v[18:21], v38, s[16:17]
	v_add_u32_e32 v39, 0x8000, v1
	global_load_dwordx4 v[22:25], v39, s[16:17]
	v_add_u32_e32 v2, 0xa000, v1
	global_load_dwordx4 v[26:29], v2, s[16:17]
	v_add_u32_e32 v3, 0xc000, v1
	global_load_dwordx4 v[30:33], v3, s[16:17]
	v_add_u32_e32 v38, 0xe000, v1
	global_load_dwordx4 v[34:37], v38, s[16:17]
	s_waitcnt vmcnt(7)
	ds_write_b128 v1, v[6:9]
	s_waitcnt vmcnt(6)
	ds_write_b128 v1, v[10:13] offset:8192
	s_waitcnt vmcnt(5)
	ds_write_b128 v1, v[14:17] offset:16384
	s_waitcnt vmcnt(4)
	ds_write_b128 v1, v[18:21] offset:24576
	s_waitcnt vmcnt(3)
	ds_write_b128 v1, v[22:25] offset:32768
	s_waitcnt vmcnt(2)
	ds_write_b128 v1, v[26:29] offset:40960
	s_waitcnt vmcnt(1)
	ds_write_b128 v1, v[30:33] offset:49152
	s_waitcnt vmcnt(0)
	ds_write_b128 v1, v[34:37] offset:57344
.LBB0_1028:
	s_or_b64 exec, exec, s[2:3]
	v_ashrrev_i32_e32 v0, 6, v5
	v_readlane_b32 s0, v251, 13
	s_lshr_b32 s0, s0, 3
	s_and_b32 s1, s0, 7
	s_lshl_b32 s1, s1, 5
	s_lshr_b32 s0, s0, 3
	s_or_b32 s0, s0, s1
	s_lshl_b32 s0, s0, 3
	s_waitcnt lgkmcnt(0)
	s_barrier
	v_add_u32_e32 v1, s0, v0
	s_movk_i32 s0, 0x1000
	v_cmp_gt_i32_e32 vcc, s0, v1
	s_and_saveexec_b64 s[2:3], vcc
	s_cbranch_execz .LBB0_1039
	s_add_u32 s4, s4, 0x22b6e000
	s_addc_u32 s5, s5, 0
	v_readlane_b32 s0, v250, 0
	s_add_u32 s0, s6, s0
	s_addc_u32 s1, s7, 0
	s_add_u32 s6, s0, 0x324000
	s_addc_u32 s7, s1, 0
	s_add_u32 s8, s8, 0x23b6e000
	s_addc_u32 s9, s9, 0
	v_and_b32_e32 v0, 63, v4
	s_add_u32 s10, s10, 0x23bae000
	v_lshlrev_b32_e32 v2, 2, v0
	s_addc_u32 s11, s11, 0
	v_lshlrev_b32_e32 v3, 2, v197
	s_add_i32 s0, 0, 0x4000
	v_add_u32_e32 v6, 0, v2
	v_lshlrev_b32_e32 v7, 7, v0
	v_and_b32_e32 v8, 0x100, v3
	v_add_u32_e32 v9, s0, v2
	s_mov_b64 s[12:13], 0
	v_lshlrev_b32_e32 v2, 2, v0
	s_branch .LBB0_1031

.LBB0_1034:
	v_add_u32_e32 v11, s0, v8
	ds_bpermute_b32 v14, v11, v10
	ds_read2st64_b32 v[12:13], v3 offset1:1
	s_add_i32 s0, s0, 32
	s_cmpk_eq_i32 s0, 0x100
	s_waitcnt lgkmcnt(0)
	v_fmac_f32_e32 v5, v12, v14
	ds_bpermute_b32 v12, v11, v10 offset:4
	ds_bpermute_b32 v14, v11, v10 offset:8
	s_waitcnt lgkmcnt(1)
	v_fmac_f32_e32 v5, v13, v12
	ds_read2st64_b32 v[12:13], v3 offset0:2 offset1:3
	s_waitcnt lgkmcnt(0)
	v_fmac_f32_e32 v5, v12, v14
	ds_bpermute_b32 v12, v11, v10 offset:12
	ds_bpermute_b32 v14, v11, v10 offset:16
	s_waitcnt lgkmcnt(1)
	v_fmac_f32_e32 v5, v13, v12
	ds_read2st64_b32 v[12:13], v3 offset0:4 offset1:5
	s_waitcnt lgkmcnt(0)
	v_fmac_f32_e32 v5, v12, v14
	ds_bpermute_b32 v12, v11, v10 offset:20
	ds_bpermute_b32 v14, v11, v10 offset:24
	ds_bpermute_b32 v11, v11, v10 offset:28
	s_waitcnt lgkmcnt(2)
	v_fmac_f32_e32 v5, v13, v12
	ds_read2st64_b32 v[12:13], v3 offset0:6 offset1:7
	v_add_u32_e32 v3, 0x800, v3
	s_waitcnt lgkmcnt(0)
	v_fmac_f32_e32 v5, v12, v14
	v_fmac_f32_e32 v5, v13, v11
	s_cbranch_scc0 .LBB0_1034
	v_and_b32_e32 v10, 0x7f, v1
	s_movk_i32 s0, 0x7f
	v_cmp_ne_u32_e32 vcc, s0, v10
	s_movk_i32 s0, 0x7ff
	s_nop 0
	v_cndmask_b32_e32 v3, 0, v5, vcc
	v_cmp_lt_u32_e32 vcc, s0, v1
	v_cvt_pk_bf16_f32 v3, v3, v93
	s_and_saveexec_b64 s[0:1], vcc
	s_xor_b64 s[14:15], exec, s[0:1]
	v_lshlrev_b32_e32 v4, 6, v4
	v_and_b32_e32 v4, 0x1e000, v4
	v_or3_b32 v92, v4, v7, v10
	s_or_saveexec_b64 s[14:15], s[14:15]
	v_mov_b64_e32 v[4:5], s[10:11]
	s_xor_b64 exec, exec, s[14:15]
	s_cbranch_execz .LBB0_1030
	v_lshl_or_b32 v92, v1, 6, v0
	v_mov_b64_e32 v[4:5], s[8:9]
	s_branch .LBB0_1030
.LBB0_1039:
	s_or_b64 exec, exec, s[2:3]
	s_mov_b64 s[4:5], s[68:69]
	s_waitcnt vmcnt(0)
	s_barrier
	s_and_saveexec_b64 s[0:1], s[70:71]
	s_xor_b64 s[2:3], exec, s[0:1]
	s_cbranch_execz .LBB0_1092
	v_writelane_b32 v250, s8, 44
	v_writelane_b32 v250, s9, 45
	v_writelane_b32 v250, s10, 46
	v_writelane_b32 v250, s11, 47
	v_writelane_b32 v250, s12, 48
	v_writelane_b32 v250, s13, 49
	v_writelane_b32 v250, s14, 50
	v_writelane_b32 v250, s15, 51
	s_load_dwordx2 s[8:9], s[68:69], 0xb8
	v_readfirstlane_b32 s12, v0
	v_readfirstlane_b32 s13, v1
	v_readlane_b32 s10, v250, 63
	v_readlane_b32 s11, v250, 61
	v_readlane_b32 s14, v250, 59
	v_mov_b32_e32 v0, 0
	s_mov_b32 s15, 0
	s_waitcnt lgkmcnt(0)
	s_add_u32 s8, s8, s10
	s_addc_u32 s9, s9, 0
	s_cmp_lg_u32 s11, 0
	s_cbranch_scc1 .Lgb6_known
	global_load_dword v1, v0, s[8:9] offset:128 sc1
	s_waitcnt vmcnt(0)
	v_readfirstlane_b32 s10, v1
	s_sub_u32 s11, s10, 1
	s_and_b32 s11, s11, s10
	s_cmp_eq_u32 s11, 0
	s_cselect_b32 s11, 2, 1
	s_cmp_eq_u32 s10, 0
	s_cselect_b32 s11, 1, s11
	v_writelane_b32 v250, s11, 61
	s_nop 0

.Lgb6_done:
	v_mov_b32_e32 v0, s12
	v_mov_b32_e32 v1, s13
	v_readlane_b32 s8, v250, 44
	v_readlane_b32 s9, v250, 45
	v_readlane_b32 s10, v250, 46
	v_readlane_b32 s11, v250, 47
	v_readlane_b32 s12, v250, 48
	v_readlane_b32 s13, v250, 49
	v_readlane_b32 s14, v250, 50
	v_readlane_b32 s15, v250, 51
.LBB0_1092:
	s_or_b64 exec, exec, s[2:3]
	v_mov_b32_e32 v149, v196
	s_waitcnt lgkmcnt(0)
	s_barrier
	s_load_dwordx2 s[2:3], s[68:69], 0xb8
	v_readlane_b32 s1, v251, 26
	v_bfe_u32 v0, v149, 3, 1
	v_readfirstlane_b32 s0, v149
	v_lshl_add_u32 v3, v0, 2, s1
	s_movk_i32 s1, 0x3ff
	v_cmp_lt_i32_e32 vcc, s1, v149
	s_movk_i32 s1, 0x400
	v_cmp_gt_i32_e64 s[4:5], s1, v149
	s_ashr_i32 s0, s0, 6
	s_waitcnt lgkmcnt(0)
	s_add_u32 s1, s2, 0x23b6e000
	v_writelane_b32 v250, s4, 12
	v_and_b32_e32 v214, 31, v149
	v_bfe_u32 v2, v149, 4, 2
	v_writelane_b32 v250, s5, 13
	v_writelane_b32 v250, s1, 14
	s_addc_u32 s1, s3, 0
	v_writelane_b32 v250, s1, 15
	s_add_u32 s1, s2, 0x23bae000
	v_writelane_b32 v250, s1, 16
	s_addc_u32 s1, s3, 0
	v_writelane_b32 v250, s1, 17
	v_cmp_eq_u32_e64 s[4:5], 0, v149
	v_and_b32_e32 v1, 63, v149
	v_and_b32_e32 v159, 7, v149
	v_writelane_b32 v250, s4, 18
	s_mov_b32 s1, 0
	v_cmp_eq_u32_e64 s[8:9], 0, v214
	v_writelane_b32 v250, s5, 19
	s_lshl_b32 s4, s0, 2
	v_writelane_b32 v250, s4, 20
	v_or_b32_e32 v213, s4, v0
	s_add_u32 s4, s2, 0x1a86c000
	v_writelane_b32 v250, s4, 21
	s_addc_u32 s4, s3, 0
	v_writelane_b32 v250, s4, 22
	s_add_u32 s4, s2, 0x2286e000
	s_addc_u32 s5, s3, 0
	v_writelane_b32 v250, s4, 23
	v_lshlrev_b32_e32 v0, 3, v2
	v_cmp_eq_u32_e64 s[10:11], 0, v1
	v_writelane_b32 v250, s5, 24
	s_add_u32 s4, s2, 0x23bee000
	s_addc_u32 s5, s3, 0
	v_writelane_b32 v250, s4, 25
	s_lshl_b32 s0, s0, 4
	v_lshlrev_b32_e32 v148, 2, v2
	v_writelane_b32 v250, s5, 26
	s_add_u32 s4, s2, 0x2186e000
	v_writelane_b32 v250, s4, 27
	s_addc_u32 s4, s3, 0
	v_writelane_b32 v250, s4, 28
	s_add_u32 s4, s2, 0x21c6e000
	v_writelane_b32 v250, s4, 29
	s_addc_u32 s4, s3, 0
	v_writelane_b32 v250, s4, 30
	s_add_u32 s4, s2, 0x2206e000
	v_writelane_b32 v250, s4, 31
	s_addc_u32 s4, s3, 0
	v_writelane_b32 v250, s4, 32
	s_add_u32 s4, s2, 0x2246e000
	v_writelane_b32 v250, s4, 33
	s_addc_u32 s4, s3, 0
	s_add_u32 s2, s2, 0x1f06c000
	v_writelane_b32 v250, s4, 34
	s_addc_u32 s3, s3, 0
	v_writelane_b32 v250, s2, 35
	v_cmp_lt_u32_e64 s[16:17], 3, v214
	v_cmp_lt_u32_e64 s[18:19], 4, v214
	v_writelane_b32 v250, s3, 36
	v_cmp_lt_u32_e64 s[2:3], 1, v214
	v_cmp_lt_u32_e64 s[20:21], 5, v214
	v_cmp_lt_u32_e64 s[22:23], 6, v214
	v_writelane_b32 v250, s2, 37
	v_cmp_lt_u32_e64 s[24:25], 7, v214
	v_cmp_lt_u32_e64 s[26:27], 8, v214
	v_writelane_b32 v250, s3, 38
	v_cmp_lt_u32_e64 s[2:3], 2, v214
	v_cmp_lt_u32_e64 s[28:29], 9, v214
	v_cmp_lt_u32_e64 s[30:31], 10, v214
	v_writelane_b32 v250, s2, 39
	v_cmp_lt_u32_e64 s[34:35], 11, v214
	v_cmp_lt_u32_e64 s[36:37], 12, v214
	v_writelane_b32 v250, s3, 40
	s_xor_b64 s[2:3], vcc, -1
	v_cmp_lt_u32_e64 s[38:39], 13, v214
	v_cmp_lt_u32_e64 s[40:41], 14, v214
	v_cmp_lt_u32_e64 s[42:43], 15, v214
	v_cmp_lt_u32_e64 s[44:45], 16, v214
	v_cmp_lt_u32_e64 s[46:47], 17, v214
	v_cmp_lt_u32_e64 s[48:49], 18, v214
	v_cmp_lt_u32_e64 s[50:51], 19, v214
	v_cmp_lt_u32_e64 s[52:53], 20, v214
	v_cmp_lt_u32_e64 s[54:55], 21, v214
	v_cmp_lt_u32_e64 s[56:57], 22, v214
	v_cmp_lt_u32_e64 s[58:59], 23, v214
	v_cmp_lt_u32_e64 s[60:61], 24, v214
	v_cmp_lt_u32_e64 s[62:63], 25, v214
	v_cmp_lt_u32_e64 s[64:65], 26, v214
	v_cmp_lt_u32_e64 s[66:67], 27, v214
	v_cmp_lt_u32_e64 s[68:69], 28, v214
	v_lshlrev_b32_e32 v215, 3, v149
	s_mov_b32 s4, -1
	v_writelane_b32 v250, s2, 41
	v_lshlrev_b32_e32 v150, 1, v0
	v_add_u32_e32 v216, s0, v3
	s_mov_b32 s6, 0
	v_cmp_lt_u32_e64 s[70:71], 29, v214
	v_cmp_eq_u32_e64 s[72:73], 31, v214
	v_writelane_b32 v250, s3, 42
	s_branch .LBB0_1096
